# grid barrier: arrivers 8 and 24 of each XCD start an extra un-waited L2 write-back (on v59)
# baseline (speedup 1.0000x reference)
; __device__ __forceinline__ unsigned xb_ld(unsigned* p)              { return __hip_atomic_load(p, __ATOMIC_RELAXED, __HIP_MEMORY_SCOPE_AGENT); }
; __device__ __forceinline__ unsigned xb_add(unsigned* p, unsigned v) { return __hip_atomic_fetch_add(p, v, __ATOMIC_RELAXED, __HIP_MEMORY_SCOPE_AGENT); }
; #define XB_SPIN(cond, bar) do { unsigned _sp = 0; while (cond) { __builtin_amdgcn_s_sleep(1); \
;     if ((++_sp & 255u) == 0u) { if (xb_ld(&(bar)[XB_TMO])) break; if (_sp > XB_SPIN_CAP) { atomicAdd(&(bar)[XB_TMO], 1u); break; } } } } while (0)
; __device__ __forceinline__ void grid_bar(const Ctx& F, unsigned) {
;     ...
;             const unsigned old = xb_add(&bar[XB_XSUB(x)], 1u);
;             const unsigned gen = old / nloc;
;             if (old + 1u == (gen + 1u) * nloc) {
;                 __builtin_amdgcn_fence(__ATOMIC_RELEASE, "agent");
;                 asm volatile("s_waitcnt vmcnt(0)" ::: "memory");
;                 const unsigned og = xb_add(&bar[XB_TOP], 1u);
;                 const unsigned tg = og / nx;
;                 if (og + 1u == (tg + 1u) * nx) xb_add(&bar[XB_TOPGEN], 1u);
;                 else XB_SPIN(xb_ld(&bar[XB_TOPGEN]) == tg, bar);
;                 __builtin_amdgcn_fence(__ATOMIC_ACQUIRE, "agent");
;                 xb_add(&bar[XB_XGEN(x)], 1u);
;                 asm volatile("s_waitcnt vmcnt(0)" ::: "memory");
;             } else {
;                 XB_SPIN(xb_ld(&bar[XB_XGEN(x)]) == gen, bar);
.LBB0_186:
	s_or_b64 exec, exec, s[12:13]
	v_cvt_f32_u32_e32 v4, v2
	s_waitcnt vmcnt(0)
	v_readfirstlane_b32 s0, v3
	s_and_b32 s32, s0, 15
	s_cmp_lg_u32 s32, 8
	s_cbranch_scc1 .Lwb_skip0
	buffer_wbl2 sc1
.Lwb_skip0:
	v_sub_u32_e32 v3, 0, v2
	v_rcp_iflag_f32_e32 v4, v4
	v_add_u32_e32 v5, s0, v1
	v_mul_f32_e32 v4, 0x4f7ffffe, v4
	v_cvt_u32_f32_e32 v4, v4
	v_mul_lo_u32 v1, v3, v4
	v_mul_hi_u32 v1, v4, v1
	v_add_u32_e32 v1, v4, v1
	v_mul_hi_u32 v1, v5, v1
	v_mul_lo_u32 v3, v1, v2
	v_sub_u32_e32 v3, v5, v3
	v_add_u32_e32 v4, 1, v1
	v_cmp_ge_u32_e32 vcc, v3, v2
	s_nop 1
	v_cndmask_b32_e32 v1, v1, v4, vcc
	v_sub_u32_e32 v4, v3, v2
	v_cndmask_b32_e32 v3, v3, v4, vcc
	v_add_u32_e32 v4, 1, v1
	v_cmp_ge_u32_e32 vcc, v3, v2
	v_add_u32_e32 v3, 1, v5
	s_nop 0
	v_cndmask_b32_e32 v1, v1, v4, vcc
	v_mul_lo_u32 v4, v2, v1
	v_add_u32_e32 v2, v4, v2
	v_cmp_ne_u32_e32 vcc, v3, v2
	s_and_saveexec_b64 s[0:1], vcc
	s_xor_b64 s[10:11], exec, s[0:1]
	s_cbranch_execz .LBB0_200
	s_waitcnt lgkmcnt(0)
	v_mov_b32_e32 v0, 0x2000
	global_load_dword v0, v0, s[8:9] offset:1024 sc1
	s_add_u32 s14, s8, 0x2400
	s_addc_u32 s15, s9, 0
	s_waitcnt vmcnt(0)
	v_cmp_eq_u32_e32 vcc, v0, v1
	s_and_saveexec_b64 s[12:13], vcc
	s_cbranch_execz .LBB0_199
	s_mov_b32 s0, 1
	s_mov_b64 s[16:17], 0
	v_mov_b32_e32 v0, 0
	s_branch .LBB0_190

; __device__ __forceinline__ unsigned xb_ld(unsigned* p)              { return __hip_atomic_load(p, __ATOMIC_RELAXED, __HIP_MEMORY_SCOPE_AGENT); }
; __device__ __forceinline__ unsigned xb_add(unsigned* p, unsigned v) { return __hip_atomic_fetch_add(p, v, __ATOMIC_RELAXED, __HIP_MEMORY_SCOPE_AGENT); }
; #define XB_SPIN(cond, bar) do { unsigned _sp = 0; while (cond) { __builtin_amdgcn_s_sleep(1); \
;     if ((++_sp & 255u) == 0u) { if (xb_ld(&(bar)[XB_TMO])) break; if (_sp > XB_SPIN_CAP) { atomicAdd(&(bar)[XB_TMO], 1u); break; } } } } while (0)
; __device__ __forceinline__ void grid_bar(const Ctx& F, unsigned) {
;     ...
;             const unsigned old = xb_add(&bar[XB_XSUB(x)], 1u);
;             const unsigned gen = old / nloc;
;             if (old + 1u == (gen + 1u) * nloc) {
;                 __builtin_amdgcn_fence(__ATOMIC_RELEASE, "agent");
;                 asm volatile("s_waitcnt vmcnt(0)" ::: "memory");
;                 const unsigned og = xb_add(&bar[XB_TOP], 1u);
;                 const unsigned tg = og / nx;
;                 if (og + 1u == (tg + 1u) * nx) xb_add(&bar[XB_TOPGEN], 1u);
;                 else XB_SPIN(xb_ld(&bar[XB_TOPGEN]) == tg, bar);
;                 __builtin_amdgcn_fence(__ATOMIC_ACQUIRE, "agent");
;                 xb_add(&bar[XB_XGEN(x)], 1u);
;                 asm volatile("s_waitcnt vmcnt(0)" ::: "memory");
;             } else {
;                 XB_SPIN(xb_ld(&bar[XB_XGEN(x)]) == gen, bar);
.LBB0_1784:
	s_or_b64 exec, exec, s[8:9]
	v_cvt_f32_u32_e32 v4, v2
	s_waitcnt vmcnt(0)
	v_readfirstlane_b32 s6, v3
	s_and_b32 s32, s6, 15
	s_cmp_lg_u32 s32, 8
	s_cbranch_scc1 .Lwb_skip16
	buffer_wbl2 sc1
.Lwb_skip16:
	v_sub_u32_e32 v3, 0, v2
	v_rcp_iflag_f32_e32 v4, v4
	v_add_u32_e32 v5, s6, v1
	v_mul_f32_e32 v4, 0x4f7ffffe, v4
	v_cvt_u32_f32_e32 v4, v4
	v_mul_lo_u32 v1, v3, v4
	v_mul_hi_u32 v1, v4, v1
	v_add_u32_e32 v1, v4, v1
	v_mul_hi_u32 v1, v5, v1
	v_mul_lo_u32 v3, v1, v2
	v_sub_u32_e32 v3, v5, v3
	v_add_u32_e32 v4, 1, v1
	v_cmp_ge_u32_e32 vcc, v3, v2
	s_nop 1
	v_cndmask_b32_e32 v1, v1, v4, vcc
	v_sub_u32_e32 v4, v3, v2
	v_cndmask_b32_e32 v3, v3, v4, vcc
	v_add_u32_e32 v4, 1, v1
	v_cmp_ge_u32_e32 vcc, v3, v2
	v_add_u32_e32 v3, 1, v5
	s_nop 0
	v_cndmask_b32_e32 v1, v1, v4, vcc
	v_mul_lo_u32 v4, v2, v1
	v_add_u32_e32 v2, v4, v2
	v_cmp_ne_u32_e32 vcc, v3, v2
	s_and_saveexec_b64 s[6:7], vcc
	s_xor_b64 s[6:7], exec, s[6:7]
	s_cbranch_execz .LBB0_1798
	s_waitcnt lgkmcnt(0)
	v_mov_b32_e32 v0, 0x2000
	global_load_dword v0, v0, s[4:5] offset:1024 sc1
	s_add_u32 s10, s4, 0x2400
	s_addc_u32 s11, s5, 0
	s_waitcnt vmcnt(0)
	v_cmp_eq_u32_e32 vcc, v0, v1
	s_and_saveexec_b64 s[8:9], vcc
	s_cbranch_execz .LBB0_1797
	s_mov_b32 s22, 1
	s_mov_b64 s[12:13], 0
	v_mov_b32_e32 v0, 0
	s_branch .LBB0_1788
